# nt hint also on the one-shot w_mod GEMV loads, f32 cache loads, and the last read of the f32 inputs in R1_0
# speedup vs baseline: 1.0345x; 1.0234x over previous
.LBB0_33:
	s_add_i32 s10, s2, s3
	s_lshl_b64 s[14:15], s[10:11], 12
	v_lshl_add_u64 v[8:9], s[14:15], 0, v[144:145]
	v_lshl_add_u64 v[4:5], v[8:9], 2, s[8:9]
	global_load_dwordx4 v[0:3], v[4:5], off nt
	s_nop 0
	global_load_dwordx4 v[4:7], v[4:5], off offset:16 nt
	v_lshl_add_u64 v[8:9], v[8:9], 1, s[6:7]
	s_mov_b64 s[6:7], 0
	s_waitcnt vmcnt(1)
	v_cvt_pk_bf16_f32 v0, v0, v1
	v_cvt_pk_bf16_f32 v1, v2, v3
	s_waitcnt vmcnt(0)
	v_cvt_pk_bf16_f32 v2, v4, v5
	v_cvt_pk_bf16_f32 v3, v6, v7
	global_store_dwordx4 v[8:9], v[0:3], off sc1

.LBB0_54:
	v_lshl_add_u64 v[46:47], v[44:45], 0, s[8:9]
	s_movk_i32 s7, 0x6000
	v_add_co_u32_e32 v68, vcc, s7, v46
	s_mov_b32 s7, 0xc000
	s_nop 0
	v_addc_co_u32_e32 v69, vcc, 0, v47, vcc
	v_add_co_u32_e32 v72, vcc, s7, v46
	s_mov_b32 s7, 0x12000
	s_nop 0
	v_addc_co_u32_e32 v73, vcc, 0, v47, vcc
	v_add_co_u32_e32 v76, vcc, s7, v46
	s_mov_b32 s7, 0x18000
	s_nop 0
	v_addc_co_u32_e32 v77, vcc, 0, v47, vcc
	global_load_dwordx4 v[64:67], v[46:47], off nt
	v_add_co_u32_e32 v80, vcc, s7, v46
	s_mov_b32 s7, 0x1e000
	s_nop 0
	v_addc_co_u32_e32 v81, vcc, 0, v47, vcc
	v_add_co_u32_e32 v84, vcc, s7, v46
	s_mov_b32 s7, 0x24000
	s_nop 0
	v_addc_co_u32_e32 v85, vcc, 0, v47, vcc
	v_add_co_u32_e32 v88, vcc, s7, v46
	s_mov_b32 s7, 0x2a000
	s_nop 0
	v_addc_co_u32_e32 v89, vcc, 0, v47, vcc
	v_add_co_u32_e32 v46, vcc, s7, v46
	s_add_u32 s8, s8, 0x30000
	s_nop 0
	v_addc_co_u32_e32 v47, vcc, 0, v47, vcc
	global_load_dwordx4 v[68:71], v[68:69], off nt
	s_nop 0
	global_load_dwordx4 v[72:75], v[72:73], off nt
	s_nop 0
	global_load_dwordx4 v[76:79], v[76:77], off nt
	s_nop 0
	global_load_dwordx4 v[80:83], v[80:81], off nt
	s_nop 0
	global_load_dwordx4 v[84:87], v[84:85], off nt
	s_nop 0
	global_load_dwordx4 v[88:91], v[88:89], off nt
	s_nop 0
	global_load_dwordx4 v[92:95], v[46:47], off nt
	ds_read_b128 v[96:99], v12
	ds_read_b128 v[100:103], v12 offset:16
	ds_read_b128 v[104:107], v12 offset:4096
	ds_read_b128 v[108:111], v12 offset:4112
	ds_read_b128 v[112:115], v12 offset:8192
	ds_read_b128 v[116:119], v12 offset:8208
	s_waitcnt lgkmcnt(5)
	v_mov_b32_e32 v46, v99
	s_waitcnt lgkmcnt(3)
	v_mov_b32_e32 v120, v107
	s_addc_u32 s9, s9, 0
	s_waitcnt lgkmcnt(1)
	v_mov_b32_e32 v122, v115
	v_mov_b32_e32 v124, v103
	v_mov_b32_e32 v126, v111
	s_waitcnt lgkmcnt(0)
	v_mov_b32_e32 v128, v119
	v_add_u32_e32 v12, 32, v12
	s_cmp_eq_u32 s8, 0xc0000
	s_waitcnt vmcnt(7)
	v_pk_fma_f32 v[2:3], v[66:67], v[96:97], v[2:3] op_sel_hi:[1,0,1]
	v_pk_fma_f32 v[0:1], v[64:65], v[96:97], v[0:1] op_sel_hi:[1,0,1]
	v_pk_fma_f32 v[6:7], v[66:67], v[104:105], v[6:7] op_sel_hi:[1,0,1]
	v_pk_fma_f32 v[4:5], v[64:65], v[104:105], v[4:5] op_sel_hi:[1,0,1]
	v_pk_fma_f32 v[10:11], v[66:67], v[112:113], v[10:11] op_sel_hi:[1,0,1]
	v_pk_fma_f32 v[8:9], v[64:65], v[112:113], v[8:9] op_sel_hi:[1,0,1]
	s_waitcnt vmcnt(6)
	v_pk_fma_f32 v[0:1], v[68:69], v[96:97], v[0:1] op_sel:[0,1,0]
	v_pk_fma_f32 v[2:3], v[70:71], v[96:97], v[2:3] op_sel:[0,1,0]
	v_pk_fma_f32 v[4:5], v[68:69], v[104:105], v[4:5] op_sel:[0,1,0]
	v_pk_fma_f32 v[6:7], v[70:71], v[104:105], v[6:7] op_sel:[0,1,0]
	v_pk_fma_f32 v[8:9], v[68:69], v[112:113], v[8:9] op_sel:[0,1,0]
	v_pk_fma_f32 v[10:11], v[70:71], v[112:113], v[10:11] op_sel:[0,1,0]
	s_waitcnt vmcnt(5)
	v_pk_fma_f32 v[2:3], v[74:75], v[98:99], v[2:3] op_sel_hi:[1,0,1]
	v_pk_fma_f32 v[0:1], v[72:73], v[98:99], v[0:1] op_sel_hi:[1,0,1]
	v_pk_fma_f32 v[6:7], v[74:75], v[106:107], v[6:7] op_sel_hi:[1,0,1]
	v_pk_fma_f32 v[4:5], v[72:73], v[106:107], v[4:5] op_sel_hi:[1,0,1]
	v_pk_fma_f32 v[10:11], v[74:75], v[114:115], v[10:11] op_sel_hi:[1,0,1]
	v_pk_fma_f32 v[8:9], v[72:73], v[114:115], v[8:9] op_sel_hi:[1,0,1]
	s_waitcnt vmcnt(4)
	v_pk_fma_f32 v[2:3], v[78:79], v[46:47], v[2:3] op_sel_hi:[1,0,1]
	v_pk_fma_f32 v[0:1], v[76:77], v[46:47], v[0:1] op_sel_hi:[1,0,1]
	v_pk_fma_f32 v[6:7], v[78:79], v[120:121], v[6:7] op_sel_hi:[1,0,1]
	v_pk_fma_f32 v[4:5], v[76:77], v[120:121], v[4:5] op_sel_hi:[1,0,1]
	v_pk_fma_f32 v[10:11], v[78:79], v[122:123], v[10:11] op_sel_hi:[1,0,1]
	v_pk_fma_f32 v[8:9], v[76:77], v[122:123], v[8:9] op_sel_hi:[1,0,1]
	s_waitcnt vmcnt(3)
	v_pk_fma_f32 v[2:3], v[82:83], v[100:101], v[2:3] op_sel_hi:[1,0,1]
	v_pk_fma_f32 v[0:1], v[80:81], v[100:101], v[0:1] op_sel_hi:[1,0,1]
	v_pk_fma_f32 v[6:7], v[82:83], v[108:109], v[6:7] op_sel_hi:[1,0,1]
	v_pk_fma_f32 v[4:5], v[80:81], v[108:109], v[4:5] op_sel_hi:[1,0,1]
	v_pk_fma_f32 v[10:11], v[82:83], v[116:117], v[10:11] op_sel_hi:[1,0,1]
	v_pk_fma_f32 v[8:9], v[80:81], v[116:117], v[8:9] op_sel_hi:[1,0,1]
	s_waitcnt vmcnt(2)
	v_pk_fma_f32 v[2:3], v[86:87], v[100:101], v[2:3] op_sel:[0,1,0]
	v_pk_fma_f32 v[0:1], v[84:85], v[100:101], v[0:1] op_sel:[0,1,0]
	v_pk_fma_f32 v[6:7], v[86:87], v[108:109], v[6:7] op_sel:[0,1,0]
	v_pk_fma_f32 v[4:5], v[84:85], v[108:109], v[4:5] op_sel:[0,1,0]
	v_pk_fma_f32 v[10:11], v[86:87], v[116:117], v[10:11] op_sel:[0,1,0]
	v_pk_fma_f32 v[8:9], v[84:85], v[116:117], v[8:9] op_sel:[0,1,0]
	s_waitcnt vmcnt(1)
	v_pk_fma_f32 v[2:3], v[90:91], v[102:103], v[2:3] op_sel_hi:[1,0,1]
	v_pk_fma_f32 v[0:1], v[88:89], v[102:103], v[0:1] op_sel_hi:[1,0,1]
	v_pk_fma_f32 v[6:7], v[90:91], v[110:111], v[6:7] op_sel_hi:[1,0,1]
	v_pk_fma_f32 v[4:5], v[88:89], v[110:111], v[4:5] op_sel_hi:[1,0,1]
	v_pk_fma_f32 v[10:11], v[90:91], v[118:119], v[10:11] op_sel_hi:[1,0,1]
	v_pk_fma_f32 v[8:9], v[88:89], v[118:119], v[8:9] op_sel_hi:[1,0,1]
	s_waitcnt vmcnt(0)
	v_pk_fma_f32 v[2:3], v[94:95], v[124:125], v[2:3] op_sel_hi:[1,0,1]
	v_pk_fma_f32 v[0:1], v[92:93], v[124:125], v[0:1] op_sel_hi:[1,0,1]
	v_pk_fma_f32 v[6:7], v[94:95], v[126:127], v[6:7] op_sel_hi:[1,0,1]
	v_pk_fma_f32 v[4:5], v[92:93], v[126:127], v[4:5] op_sel_hi:[1,0,1]
	v_pk_fma_f32 v[10:11], v[94:95], v[128:129], v[10:11] op_sel_hi:[1,0,1]
	v_pk_fma_f32 v[8:9], v[92:93], v[128:129], v[8:9] op_sel_hi:[1,0,1]
	s_cbranch_scc0 .LBB0_54
	ds_write_b128 v56, v[0:3] offset:12288
	ds_write_b128 v56, v[4:7] offset:12544
	ds_write_b128 v56, v[8:11] offset:12800
	s_waitcnt lgkmcnt(0)
	s_barrier
	s_and_saveexec_b64 s[8:9], s[4:5]
	s_cbranch_execz .LBB0_22
	s_mul_i32 s7, s3, 0x1800
	s_add_i32 s7, s7, s6
	v_or_b32_e32 v0, s7, v149
	v_readlane_b32 s12, v219, 9
	v_ashrrev_i32_e32 v1, 31, v0
	v_readlane_b32 s14, v219, 11
	v_readlane_b32 s15, v219, 12
	v_readlane_b32 s13, v219, 10
	v_readlane_b32 s16, v219, 13
	v_lshl_add_u64 v[0:1], v[0:1], 2, s[14:15]
	global_load_dword v12, v[0:1], off
	ds_read2st64_b32 v[0:1], v58 offset0:48 offset1:51
	ds_read2st64_b32 v[2:3], v58 offset0:54 offset1:57
	ds_read2st64_b32 v[4:5], v58 offset0:60 offset1:63
	ds_read2st64_b32 v[6:7], v58 offset0:66 offset1:69
	ds_read2st64_b32 v[8:9], v58 offset0:72 offset1:75
	ds_read2st64_b32 v[10:11], v58 offset0:78 offset1:81
	ds_read2st64_b32 v[44:45], v58 offset0:84 offset1:87
	ds_read2st64_b32 v[46:47], v58 offset0:90 offset1:93
	ds_read2st64_b32 v[64:65], v58 offset0:96 offset1:99
	ds_read2st64_b32 v[66:67], v58 offset0:102 offset1:105
	ds_read2st64_b32 v[68:69], v58 offset0:108 offset1:111
	ds_read2st64_b32 v[70:71], v58 offset0:114 offset1:117
	ds_read2st64_b32 v[72:73], v58 offset0:120 offset1:123
	ds_read2st64_b32 v[74:75], v58 offset0:126 offset1:129
	ds_read2st64_b32 v[76:77], v58 offset0:132 offset1:135
	ds_read2st64_b32 v[78:79], v58 offset0:138 offset1:141
	v_mad_u64_u32 v[80:81], s[14:15], s3, 3, v[148:149]
	s_movk_i32 s3, 0x1800
	v_mul_lo_u32 v25, v80, s3
	v_add_u32_e32 v25, s6, v25
	v_or_b32_e32 v80, v25, v149
	v_ashrrev_i32_e32 v81, 31, v80
	v_readlane_b32 s17, v219, 14
	v_readlane_b32 s18, v219, 15
	v_readlane_b32 s19, v219, 16
	v_readlane_b32 s20, v219, 17
	v_readlane_b32 s21, v219, 18
	v_readlane_b32 s22, v219, 19
	v_readlane_b32 s23, v219, 20
	v_readlane_b32 s24, v219, 21
	v_readlane_b32 s25, v219, 22
	v_readlane_b32 s26, v219, 23
	v_readlane_b32 s27, v219, 24
	s_waitcnt vmcnt(0) lgkmcnt(14)
	v_add_f32_e32 v0, v12, v0
	v_add_f32_e32 v0, v0, v1
	v_add_f32_e32 v0, v0, v2
	v_add_f32_e32 v0, v0, v3
	s_waitcnt lgkmcnt(13)
	v_add_f32_e32 v0, v0, v4
	v_add_f32_e32 v0, v0, v5
	s_waitcnt lgkmcnt(12)
	v_add_f32_e32 v0, v0, v6
	v_add_f32_e32 v0, v0, v7
	s_waitcnt lgkmcnt(11)
	v_add_f32_e32 v0, v0, v8
	v_add_f32_e32 v0, v0, v9
	s_waitcnt lgkmcnt(10)
	v_add_f32_e32 v0, v0, v10
	v_add_f32_e32 v0, v0, v11
	s_waitcnt lgkmcnt(9)
	v_add_f32_e32 v0, v0, v44
	v_add_f32_e32 v0, v0, v45
	s_waitcnt lgkmcnt(8)
	v_add_f32_e32 v0, v0, v46
	v_add_f32_e32 v0, v0, v47
	s_waitcnt lgkmcnt(7)
	v_add_f32_e32 v0, v0, v64
	v_add_f32_e32 v0, v0, v65
	s_waitcnt lgkmcnt(6)
	v_add_f32_e32 v0, v0, v66
	v_add_f32_e32 v0, v0, v67
	s_waitcnt lgkmcnt(5)
	v_add_f32_e32 v0, v0, v68
	v_add_f32_e32 v0, v0, v69
	s_waitcnt lgkmcnt(4)
	v_add_f32_e32 v0, v0, v70
	v_add_f32_e32 v0, v0, v71
	s_waitcnt lgkmcnt(3)
	v_add_f32_e32 v0, v0, v72
	v_add_f32_e32 v0, v0, v73
	s_waitcnt lgkmcnt(2)
	v_add_f32_e32 v0, v0, v74
	v_add_f32_e32 v0, v0, v75
	s_waitcnt lgkmcnt(1)
	v_add_f32_e32 v0, v0, v76
	v_add_f32_e32 v0, v0, v77
	s_waitcnt lgkmcnt(0)
	v_add_f32_e32 v0, v0, v78
	v_add_f32_e32 v2, v0, v79
	v_lshl_add_u64 v[0:1], v[80:81], 2, s[56:57]
	global_store_dword v[0:1], v2, off sc1
	s_branch .LBB0_22

.LBB0_568:
	s_or_b64 exec, exec, s[40:41]
	v_lshlrev_b64 v[98:99], 11, v[102:103]
	v_lshl_add_u64 v[102:103], v[66:67], 0, v[98:99]
	global_load_dwordx4 v[108:111], v[102:103], off
	global_load_dwordx4 v[112:115], v[102:103], off offset:1024
	v_lshl_add_u64 v[124:125], v[100:101], 0, v[64:65]
	global_load_dwordx4 v[100:103], v[124:125], off offset:16 nt
	global_load_dwordx4 v[116:119], v[124:125], off nt
	global_load_dwordx4 v[120:123], v[124:125], off offset:2064 nt
	s_nop 0
	global_load_dwordx4 v[124:127], v[124:125], off offset:2048 nt
	s_add_i32 s10, s10, 2
	s_cmp_eq_u32 s10, 4
	s_waitcnt vmcnt(5)
	v_and_b32_e32 v131, 0xffff0000, v110
	v_and_b32_e32 v130, 0xffff0000, v108
	v_lshlrev_b32_e32 v129, 16, v110
	v_lshlrev_b32_e32 v128, 16, v108
	v_lshlrev_b32_e32 v132, 16, v109
	v_and_b32_e32 v110, 0xffff0000, v109
	s_waitcnt vmcnt(4)
	v_lshlrev_b32_e32 v109, 16, v112
	v_lshlrev_b32_e32 v108, 16, v114
	v_and_b32_e32 v135, 0xffff0000, v112
	v_and_b32_e32 v134, 0xffff0000, v114
	v_lshlrev_b32_e32 v136, 16, v115
	v_and_b32_e32 v112, 0xffff0000, v115
	v_pk_mul_f32 v[114:115], v[130:131], v[130:131]
	v_lshlrev_b32_e32 v133, 16, v111
	v_pk_mul_f32 v[138:139], v[134:135], v[134:135]
	v_pk_fma_f32 v[114:115], v[128:129], v[128:129], v[114:115]
	v_and_b32_e32 v111, 0xffff0000, v111
	v_lshlrev_b32_e32 v137, 16, v113
	v_pk_fma_f32 v[138:139], v[108:109], v[108:109], v[138:139]
	v_pk_fma_f32 v[114:115], v[132:133], v[132:133], v[114:115]
	v_and_b32_e32 v113, 0xffff0000, v113
	v_pk_fma_f32 v[138:139], v[136:137], v[136:137], v[138:139]
	v_pk_fma_f32 v[114:115], v[110:111], v[110:111], v[114:115]
	v_pk_fma_f32 v[138:139], v[112:113], v[112:113], v[138:139]
	v_add_f32_e32 v114, v114, v115
	v_add_f32_e32 v114, v114, v139
	v_add_f32_e32 v114, v138, v114
	ds_bpermute_b32 v115, v172, v114
	v_mov_b32_e32 v139, v130
	v_mov_b32_e32 v130, v129
	v_mov_b32_e32 v129, v113
	v_mov_b32_e32 v141, v135
	s_waitcnt lgkmcnt(0)
	v_add_f32_e32 v114, v114, v115
	ds_bpermute_b32 v115, v173, v114
	s_waitcnt lgkmcnt(0)
	v_add_f32_e32 v114, v114, v115
	ds_bpermute_b32 v115, v174, v114
	s_waitcnt lgkmcnt(0)
	v_add_f32_e32 v115, v114, v115
	ds_bpermute_b32 v138, v175, v115
	v_mov_b32_e32 v114, v132
	s_waitcnt lgkmcnt(0)
	v_add_f32_e32 v132, v115, v138
	ds_bpermute_b32 v140, v176, v132
	v_mov_b32_e32 v115, v110
	v_mov_b32_e32 v138, v128
	v_mov_b32_e32 v128, v137
	v_mov_b32_e32 v137, v112
	s_waitcnt lgkmcnt(0)
	v_add_f32_e32 v110, v132, v140
	ds_bpermute_b32 v132, v177, v110
	v_mov_b32_e32 v140, v109
	s_waitcnt lgkmcnt(0)
	v_add_f32_e32 v109, v110, v132
	v_fmamk_f32 v109, v109, 0x3a800000, v106
	v_mul_f32_e32 v110, 0x4b800000, v109
	v_cmp_gt_f32_e32 vcc, s8, v109
	s_nop 1
	v_cndmask_b32_e32 v109, v109, v110, vcc
	v_rsq_f32_e32 v113, v109
	v_mov_b32_e32 v109, v134
	v_mov_b32_e32 v110, v133
	v_mul_f32_e32 v112, 0x45800000, v113
	v_cndmask_b32_e32 v112, v113, v112, vcc
	v_pk_mul_f32 v[132:133], v[112:113], v[138:139] op_sel_hi:[0,1]
	v_pk_mul_f32 v[130:131], v[112:113], v[130:131] op_sel_hi:[0,1]
	v_pk_mul_f32 v[114:115], v[112:113], v[114:115] op_sel_hi:[0,1]
	v_pk_mul_f32 v[110:111], v[112:113], v[110:111] op_sel_hi:[0,1]
	v_pk_mul_f32 v[128:129], v[112:113], v[128:129] op_sel_hi:[0,1]
	v_pk_mul_f32 v[134:135], v[112:113], v[140:141] op_sel_hi:[0,1]
	v_pk_mul_f32 v[136:137], v[112:113], v[136:137] op_sel_hi:[0,1]
	v_pk_mul_f32 v[108:109], v[112:113], v[108:109] op_sel_hi:[0,1]
	v_pk_mul_f32 v[112:113], v[4:5], v[132:133]
	v_pk_mul_f32 v[130:131], v[0:1], v[130:131]
	v_pk_mul_f32 v[132:133], v[36:37], v[134:135]
	v_pk_mul_f32 v[108:109], v[32:33], v[108:109]
	s_waitcnt vmcnt(2)
	v_pk_fma_f32 v[112:113], v[12:13], v[112:113], v[116:117]
	v_pk_fma_f32 v[116:117], v[8:9], v[130:131], v[100:101]
	v_pk_mul_f32 v[114:115], v[6:7], v[114:115]
	v_pk_mul_f32 v[110:111], v[2:3], v[110:111]
	s_waitcnt vmcnt(0)
	v_pk_fma_f32 v[124:125], v[44:45], v[132:133], v[124:125]
	v_pk_fma_f32 v[120:121], v[40:41], v[108:109], v[120:121]
	v_mov_b32_e32 v108, v113
	v_mov_b32_e32 v109, v117
	v_pk_mul_f32 v[128:129], v[38:39], v[128:129]
	v_pk_mul_f32 v[134:135], v[34:35], v[136:137]
	v_pk_fma_f32 v[114:115], v[14:15], v[114:115], v[118:119]
	v_pk_fma_f32 v[102:103], v[10:11], v[110:111], v[102:103]
	v_mov_b32_e32 v100, v112
	v_mov_b32_e32 v101, v116
	v_mov_b32_e32 v130, v121
	v_mov_b32_e32 v131, v125
	v_pk_mul_f32 v[108:109], v[108:109], v[108:109]
	v_pk_fma_f32 v[118:119], v[46:47], v[128:129], v[126:127]
	v_pk_fma_f32 v[122:123], v[42:43], v[134:135], v[122:123]
	v_mov_b32_e32 v110, v114
	v_mov_b32_e32 v111, v102
	v_mov_b32_e32 v128, v120
	v_mov_b32_e32 v129, v124
	v_pk_mul_f32 v[130:131], v[130:131], v[130:131]
	v_pk_fma_f32 v[100:101], v[100:101], v[100:101], v[108:109]
	v_mov_b32_e32 v126, v115
	v_mov_b32_e32 v127, v103
	v_mov_b32_e32 v132, v122
	v_mov_b32_e32 v133, v118
	v_pk_fma_f32 v[108:109], v[128:129], v[128:129], v[130:131]
	v_pk_fma_f32 v[100:101], v[110:111], v[110:111], v[100:101]
	v_mov_b32_e32 v134, v123
	v_mov_b32_e32 v135, v119
	v_pk_fma_f32 v[108:109], v[132:133], v[132:133], v[108:109]
	v_pk_fma_f32 v[100:101], v[126:127], v[126:127], v[100:101]
	v_pk_fma_f32 v[108:109], v[134:135], v[134:135], v[108:109]
	v_add_f32_e32 v100, v100, v101
	v_add_f32_e32 v100, v109, v100
	v_add_f32_e32 v100, v108, v100
	ds_bpermute_b32 v101, v172, v100
	v_lshl_add_u64 v[126:127], v[68:69], 0, v[98:99]
	v_lshl_add_u64 v[128:129], v[70:71], 0, v[98:99]
	v_cvt_pk_bf16_f32 v98, v112, v113
	v_cvt_pk_bf16_f32 v99, v114, v115
	s_waitcnt lgkmcnt(0)
	v_add_f32_e32 v100, v100, v101
	ds_bpermute_b32 v101, v173, v100
	v_cvt_pk_bf16_f32 v109, v118, v119
	v_cvt_pk_bf16_f32 v110, v120, v121
	s_waitcnt lgkmcnt(0)
	v_add_f32_e32 v100, v100, v101
	ds_bpermute_b32 v101, v174, v100
	s_waitcnt lgkmcnt(0)
	v_add_f32_e32 v100, v100, v101
	ds_bpermute_b32 v101, v175, v100
	s_waitcnt lgkmcnt(0)
	v_add_f32_e32 v101, v100, v101
	ds_bpermute_b32 v108, v176, v101
	v_cvt_pk_bf16_f32 v100, v116, v117
	s_waitcnt lgkmcnt(0)
	v_add_f32_e32 v111, v101, v108
	ds_bpermute_b32 v130, v177, v111
	v_cvt_pk_bf16_f32 v101, v102, v103
	v_cvt_pk_bf16_f32 v108, v124, v125
	s_waitcnt lgkmcnt(0)
	v_add_f32_e32 v111, v111, v130
	v_fmamk_f32 v111, v111, 0x3a800000, v106
	v_mul_f32_e32 v130, 0x4b800000, v111
	v_cmp_gt_f32_e32 vcc, s8, v111
	s_nop 1
	v_cndmask_b32_e32 v111, v111, v130, vcc
	v_rsq_f32_e32 v130, v111
	v_cvt_pk_bf16_f32 v111, v122, v123
	global_store_dwordx4 v[126:127], v[98:101], off sc1
	global_store_dwordx4 v[126:127], v[108:111], off offset:1024 sc1
	s_nop 0
	v_mul_f32_e32 v98, 0x45800000, v130
	v_cndmask_b32_e32 v98, v130, v98, vcc
	v_pk_mul_f32 v[100:101], v[114:115], v[98:99] op_sel_hi:[1,0]
	v_pk_mul_f32 v[108:109], v[112:113], v[98:99] op_sel_hi:[1,0]
	v_pk_mul_f32 v[102:103], v[102:103], v[98:99] op_sel_hi:[1,0]
	v_pk_mul_f32 v[110:111], v[116:117], v[98:99] op_sel_hi:[1,0]
	v_pk_mul_f32 v[112:113], v[118:119], v[98:99] op_sel_hi:[1,0]
	v_pk_mul_f32 v[114:115], v[124:125], v[98:99] op_sel_hi:[1,0]
	v_pk_mul_f32 v[116:117], v[122:123], v[98:99] op_sel_hi:[1,0]
	v_pk_mul_f32 v[98:99], v[120:121], v[98:99] op_sel_hi:[1,0]
	v_pk_mul_f32 v[108:109], v[20:21], v[108:109]
	v_pk_mul_f32 v[100:101], v[22:23], v[100:101]
	v_pk_mul_f32 v[110:111], v[16:17], v[110:111]
	v_pk_mul_f32 v[102:103], v[18:19], v[102:103]
	v_pk_mul_f32 v[114:115], v[52:53], v[114:115]
	v_pk_mul_f32 v[112:113], v[54:55], v[112:113]
	v_pk_mul_f32 v[98:99], v[48:49], v[98:99]
	v_pk_mul_f32 v[116:117], v[50:51], v[116:117]
	v_pk_fma_f32 v[100:101], v[82:83], v[100:101], v[30:31]
	v_pk_fma_f32 v[108:109], v[84:85], v[108:109], v[28:29]
	v_pk_fma_f32 v[102:103], v[86:87], v[102:103], v[26:27]
	v_pk_fma_f32 v[110:111], v[88:89], v[110:111], v[24:25]
	v_pk_fma_f32 v[112:113], v[90:91], v[112:113], v[62:63]
	v_pk_fma_f32 v[114:115], v[92:93], v[114:115], v[60:61]
	v_pk_fma_f32 v[116:117], v[94:95], v[116:117], v[58:59]
	v_pk_fma_f32 v[118:119], v[96:97], v[98:99], v[56:57]
	v_cvt_pk_bf16_f32 v98, v108, v109
	v_cvt_pk_bf16_f32 v99, v100, v101
	v_cvt_pk_bf16_f32 v100, v110, v111
	v_cvt_pk_bf16_f32 v101, v102, v103
	v_cvt_pk_bf16_f32 v108, v114, v115
	v_cvt_pk_bf16_f32 v109, v112, v113
	v_cvt_pk_bf16_f32 v110, v118, v119
	v_cvt_pk_bf16_f32 v111, v116, v117
	global_store_dwordx4 v[128:129], v[98:101], off sc1
	global_store_dwordx4 v[128:129], v[108:111], off offset:1024 sc1
	s_cbranch_scc1 .LBB0_566
.LBB0_569:
	v_add_u32_e32 v98, s10, v104
	v_cmp_lt_i32_e32 vcc, s3, v98
	s_and_saveexec_b64 s[16:17], vcc
	s_xor_b64 s[40:41], exec, s[16:17]
	v_add_u32_e32 v100, 0xfffff000, v98
	v_mov_b32_e32 v101, v65
	v_lshlrev_b64 v[100:101], 12, v[100:101]
	v_lshl_add_u64 v[102:103], s[38:39], 0, v[100:101]
	v_mov_b32_e32 v99, v65
	s_andn2_saveexec_b64 s[40:41], s[40:41]
	v_ashrrev_i32_e32 v99, 31, v98
	v_lshlrev_b64 v[100:101], 12, v[98:99]
	v_lshl_add_u64 v[102:103], s[36:37], 0, v[100:101]
	s_or_b64 exec, exec, s[40:41]
	v_lshlrev_b64 v[100:101], 11, v[98:99]
	v_lshl_add_u64 v[112:113], v[66:67], 0, v[100:101]
	global_load_dwordx4 v[108:111], v[112:113], off
	s_nop 0
	global_load_dwordx4 v[112:115], v[112:113], off offset:1024
	v_lshl_add_u64 v[102:103], v[102:103], 0, v[64:65]
	global_load_dwordx4 v[116:119], v[102:103], off offset:16 nt
	global_load_dwordx4 v[120:123], v[102:103], off nt
	global_load_dwordx4 v[124:127], v[102:103], off offset:2064 nt
	global_load_dwordx4 v[128:131], v[102:103], off offset:2048 nt
	s_waitcnt vmcnt(5)
	v_and_b32_e32 v133, 0xffff0000, v110
	v_and_b32_e32 v132, 0xffff0000, v108
	v_lshlrev_b32_e32 v103, 16, v110
	v_lshlrev_b32_e32 v102, 16, v108
	v_lshlrev_b32_e32 v134, 16, v109
	v_and_b32_e32 v110, 0xffff0000, v109
	s_waitcnt vmcnt(4)
	v_lshlrev_b32_e32 v109, 16, v112
	v_lshlrev_b32_e32 v108, 16, v114
	v_and_b32_e32 v137, 0xffff0000, v112
	v_and_b32_e32 v136, 0xffff0000, v114
	v_lshlrev_b32_e32 v138, 16, v115
	v_and_b32_e32 v112, 0xffff0000, v115
	v_pk_mul_f32 v[114:115], v[132:133], v[132:133]
	v_lshlrev_b32_e32 v135, 16, v111
	v_pk_mul_f32 v[140:141], v[136:137], v[136:137]
	v_pk_fma_f32 v[114:115], v[102:103], v[102:103], v[114:115]
	v_and_b32_e32 v111, 0xffff0000, v111
	v_lshlrev_b32_e32 v139, 16, v113
	v_pk_fma_f32 v[140:141], v[108:109], v[108:109], v[140:141]
	v_pk_fma_f32 v[114:115], v[134:135], v[134:135], v[114:115]
	v_and_b32_e32 v113, 0xffff0000, v113
	v_pk_fma_f32 v[140:141], v[138:139], v[138:139], v[140:141]
	v_pk_fma_f32 v[114:115], v[110:111], v[110:111], v[114:115]
	v_pk_fma_f32 v[140:141], v[112:113], v[112:113], v[140:141]
	v_add_f32_e32 v99, v114, v115
	v_add_f32_e32 v99, v99, v141
	v_add_f32_e32 v99, v140, v99
	ds_bpermute_b32 v114, v172, v99
	v_mov_b32_e32 v142, v109
	v_mov_b32_e32 v140, v102
	v_mov_b32_e32 v102, v139
	v_mov_b32_e32 v139, v112
	s_waitcnt lgkmcnt(0)
	v_add_f32_e32 v99, v99, v114
	ds_bpermute_b32 v114, v173, v99
	v_mov_b32_e32 v141, v132
	v_mov_b32_e32 v132, v103
	v_mov_b32_e32 v103, v113
	v_mov_b32_e32 v143, v137
	s_waitcnt lgkmcnt(0)
	v_add_f32_e32 v99, v99, v114
	ds_bpermute_b32 v114, v174, v99
	s_waitcnt lgkmcnt(0)
	v_add_f32_e32 v99, v99, v114
	ds_bpermute_b32 v115, v175, v99
	v_mov_b32_e32 v114, v134
	s_waitcnt lgkmcnt(0)
	v_add_f32_e32 v99, v99, v115
	ds_bpermute_b32 v134, v176, v99
	v_mov_b32_e32 v115, v110
	s_waitcnt lgkmcnt(0)
	v_add_f32_e32 v99, v99, v134
	ds_bpermute_b32 v110, v177, v99
	s_waitcnt lgkmcnt(0)
	v_add_f32_e32 v99, v99, v110
	v_fmamk_f32 v99, v99, 0x3a800000, v106
	v_mul_f32_e32 v109, 0x4b800000, v99
	v_cmp_gt_f32_e32 vcc, s8, v99
	v_mov_b32_e32 v110, v135
	s_nop 0
	v_cndmask_b32_e32 v99, v99, v109, vcc
	v_rsq_f32_e32 v99, v99
	v_mov_b32_e32 v109, v136
	v_mul_f32_e32 v112, 0x45800000, v99
	v_cndmask_b32_e32 v112, v99, v112, vcc
	v_pk_mul_f32 v[134:135], v[112:113], v[140:141] op_sel_hi:[0,1]
	v_pk_mul_f32 v[132:133], v[112:113], v[132:133] op_sel_hi:[0,1]
	v_pk_mul_f32 v[114:115], v[112:113], v[114:115] op_sel_hi:[0,1]
	v_pk_mul_f32 v[110:111], v[112:113], v[110:111] op_sel_hi:[0,1]
	v_pk_mul_f32 v[102:103], v[112:113], v[102:103] op_sel_hi:[0,1]
	v_pk_mul_f32 v[136:137], v[112:113], v[142:143] op_sel_hi:[0,1]
	v_pk_mul_f32 v[138:139], v[112:113], v[138:139] op_sel_hi:[0,1]
	v_pk_mul_f32 v[108:109], v[112:113], v[108:109] op_sel_hi:[0,1]
	v_pk_mul_f32 v[112:113], v[4:5], v[134:135]
	v_pk_mul_f32 v[132:133], v[0:1], v[132:133]
	v_pk_mul_f32 v[134:135], v[36:37], v[136:137]
	v_pk_mul_f32 v[108:109], v[32:33], v[108:109]
	s_waitcnt vmcnt(2)
	v_pk_fma_f32 v[120:121], v[12:13], v[112:113], v[120:121]
	v_pk_fma_f32 v[116:117], v[8:9], v[132:133], v[116:117]
	v_pk_mul_f32 v[114:115], v[6:7], v[114:115]
	v_pk_mul_f32 v[110:111], v[2:3], v[110:111]
	v_pk_mul_f32 v[102:103], v[38:39], v[102:103]
	s_waitcnt vmcnt(0)
	v_pk_fma_f32 v[128:129], v[44:45], v[134:135], v[128:129]
	v_pk_fma_f32 v[124:125], v[40:41], v[108:109], v[124:125]
	v_mov_b32_e32 v108, v121
	v_mov_b32_e32 v109, v117
	v_pk_mul_f32 v[136:137], v[34:35], v[138:139]
	v_pk_fma_f32 v[122:123], v[14:15], v[114:115], v[122:123]
	v_pk_fma_f32 v[118:119], v[10:11], v[110:111], v[118:119]
	v_pk_fma_f32 v[130:131], v[46:47], v[102:103], v[130:131]
	v_mov_b32_e32 v102, v120
	v_mov_b32_e32 v103, v116
	v_mov_b32_e32 v132, v125
	v_mov_b32_e32 v133, v129
	v_pk_mul_f32 v[108:109], v[108:109], v[108:109]
	v_pk_fma_f32 v[126:127], v[42:43], v[136:137], v[126:127]
	v_mov_b32_e32 v110, v122
	v_mov_b32_e32 v111, v118
	v_mov_b32_e32 v114, v124
	v_mov_b32_e32 v115, v128
	v_pk_mul_f32 v[132:133], v[132:133], v[132:133]
	v_pk_fma_f32 v[102:103], v[102:103], v[102:103], v[108:109]
	v_mov_b32_e32 v112, v123
	v_mov_b32_e32 v113, v119
	v_mov_b32_e32 v134, v126
	v_mov_b32_e32 v135, v130
	v_pk_fma_f32 v[108:109], v[114:115], v[114:115], v[132:133]
	v_pk_fma_f32 v[102:103], v[110:111], v[110:111], v[102:103]
	v_mov_b32_e32 v136, v127
	v_mov_b32_e32 v137, v131
	v_pk_fma_f32 v[108:109], v[134:135], v[134:135], v[108:109]
	v_pk_fma_f32 v[102:103], v[112:113], v[112:113], v[102:103]
	v_pk_fma_f32 v[108:109], v[136:137], v[136:137], v[108:109]
	v_add_f32_e32 v99, v102, v103
	v_add_f32_e32 v99, v109, v99
	v_add_f32_e32 v99, v108, v99
	ds_bpermute_b32 v102, v172, v99
	v_lshl_add_u64 v[132:133], v[68:69], 0, v[100:101]
	v_cvt_pk_bf16_f32 v108, v120, v121
	v_cvt_pk_bf16_f32 v109, v122, v123
	v_cvt_pk_bf16_f32 v110, v116, v117
	s_waitcnt lgkmcnt(0)
	v_add_f32_e32 v99, v99, v102
	ds_bpermute_b32 v102, v173, v99
	v_cvt_pk_bf16_f32 v111, v118, v119
	v_cvt_pk_bf16_f32 v112, v128, v129
	v_cvt_pk_bf16_f32 v113, v130, v131
	v_cvt_pk_bf16_f32 v114, v124, v125
	s_waitcnt lgkmcnt(0)
	v_add_f32_e32 v99, v99, v102
	ds_bpermute_b32 v102, v174, v99
	v_cvt_pk_bf16_f32 v115, v126, v127
	global_store_dwordx4 v[132:133], v[108:111], off sc1
	global_store_dwordx4 v[132:133], v[112:115], off offset:1024 sc1
	v_lshl_add_u64 v[100:101], v[70:71], 0, v[100:101]
	s_waitcnt lgkmcnt(0)
	v_add_f32_e32 v99, v99, v102
	ds_bpermute_b32 v103, v175, v99
	v_add_u32_e32 v102, 1, v98
	s_waitcnt lgkmcnt(0)
	v_add_f32_e32 v99, v99, v103
	ds_bpermute_b32 v103, v176, v99
	s_waitcnt lgkmcnt(0)
	v_add_f32_e32 v99, v99, v103
	ds_bpermute_b32 v103, v177, v99
	s_waitcnt lgkmcnt(0)
	v_add_f32_e32 v99, v99, v103
	v_fmamk_f32 v99, v99, 0x3a800000, v106
	v_mul_f32_e32 v103, 0x4b800000, v99
	v_cmp_gt_f32_e32 vcc, s8, v99
	s_nop 1
	v_cndmask_b32_e32 v99, v99, v103, vcc
	v_rsq_f32_e32 v99, v99
	s_nop 0
	v_mul_f32_e32 v103, 0x45800000, v99
	v_cndmask_b32_e32 v108, v99, v103, vcc
	v_pk_mul_f32 v[110:111], v[122:123], v[108:109] op_sel_hi:[1,0]
	v_pk_mul_f32 v[112:113], v[120:121], v[108:109] op_sel_hi:[1,0]
	v_pk_mul_f32 v[114:115], v[118:119], v[108:109] op_sel_hi:[1,0]
	v_pk_mul_f32 v[116:117], v[116:117], v[108:109] op_sel_hi:[1,0]
	v_pk_mul_f32 v[118:119], v[130:131], v[108:109] op_sel_hi:[1,0]
	v_pk_mul_f32 v[120:121], v[128:129], v[108:109] op_sel_hi:[1,0]
	v_pk_mul_f32 v[122:123], v[126:127], v[108:109] op_sel_hi:[1,0]
	v_pk_mul_f32 v[108:109], v[124:125], v[108:109] op_sel_hi:[1,0]
	v_pk_mul_f32 v[112:113], v[20:21], v[112:113]
	v_pk_mul_f32 v[110:111], v[22:23], v[110:111]
	v_pk_mul_f32 v[116:117], v[16:17], v[116:117]
	v_pk_mul_f32 v[114:115], v[18:19], v[114:115]
	v_pk_mul_f32 v[120:121], v[52:53], v[120:121]
	v_pk_mul_f32 v[118:119], v[54:55], v[118:119]
	v_pk_mul_f32 v[108:109], v[48:49], v[108:109]
	v_pk_mul_f32 v[122:123], v[50:51], v[122:123]
	v_pk_fma_f32 v[110:111], v[82:83], v[110:111], v[30:31]
	v_pk_fma_f32 v[112:113], v[84:85], v[112:113], v[28:29]
	v_pk_fma_f32 v[114:115], v[86:87], v[114:115], v[26:27]
	v_pk_fma_f32 v[116:117], v[88:89], v[116:117], v[24:25]
	v_pk_fma_f32 v[118:119], v[90:91], v[118:119], v[62:63]
	v_pk_fma_f32 v[120:121], v[92:93], v[120:121], v[60:61]
	v_pk_fma_f32 v[122:123], v[94:95], v[122:123], v[58:59]
	v_pk_fma_f32 v[124:125], v[96:97], v[108:109], v[56:57]
	v_cvt_pk_bf16_f32 v108, v112, v113
	v_cvt_pk_bf16_f32 v109, v110, v111
	v_cvt_pk_bf16_f32 v110, v116, v117
	v_cvt_pk_bf16_f32 v111, v114, v115
	v_cmp_lt_i32_e32 vcc, s3, v102
	v_cvt_pk_bf16_f32 v112, v120, v121
	v_cvt_pk_bf16_f32 v113, v118, v119
	v_cvt_pk_bf16_f32 v114, v124, v125
	v_cvt_pk_bf16_f32 v115, v122, v123
	global_store_dwordx4 v[100:101], v[108:111], off sc1
	global_store_dwordx4 v[100:101], v[112:115], off offset:1024 sc1
	s_and_saveexec_b64 s[16:17], vcc
	s_xor_b64 s[40:41], exec, s[16:17]
	v_add_u32_e32 v98, 0xfffff001, v98
	v_mov_b32_e32 v99, v65
	v_lshlrev_b64 v[98:99], 12, v[98:99]
	v_lshl_add_u64 v[100:101], s[38:39], 0, v[98:99]
	v_mov_b32_e32 v103, v65
	s_andn2_saveexec_b64 s[40:41], s[40:41]
	s_cbranch_execz .LBB0_568
	v_ashrrev_i32_e32 v103, 31, v102
	v_lshlrev_b64 v[98:99], 12, v[102:103]
	v_lshl_add_u64 v[100:101], s[36:37], 0, v[98:99]
	s_branch .LBB0_568
